# previous best + L2 write-back fence (buffer_wbl2) dropped at the P0->P1 and P2->P3 grid barriers: everything those phases hand over is written through
# baseline (speedup 1.0000x reference)
.LBB0_134:
	s_andn2_saveexec_b64 s[2:3], s[2:3]
	s_cbranch_execz .LBB0_154
	s_mov_b64 s[2:3], exec
	s_nop 0
	s_waitcnt lgkmcnt(0)
	s_waitcnt vmcnt(0)
	v_mbcnt_lo_u32_b32 v2, s2, 0
	v_mbcnt_hi_u32_b32 v2, s3, v2
	v_cmp_eq_u32_e32 vcc, 0, v2
	s_and_saveexec_b64 s[10:11], vcc
	s_cbranch_execz .LBB0_137
	s_load_dwordx4 s[12:15], s[52:53], 0x80
	s_bcnt1_i32_b64 s2, s[2:3]
	v_mov_b32_e32 v3, 0x4000
	v_mov_b32_e32 v4, s2
	s_waitcnt lgkmcnt(0)
	global_atomic_add v3, v3, v4, s[12:13] offset:1024 sc0
